# q_b/kv_b phase GEMM balance: K_KV and K_VT tiles dealt only to the 122 CUs with one K_Q tile (2-3 each), none to the CUs with two K_Q tiles
# baseline (speedup 1.0000x reference)
;     __device__ bool next(int i, Unit& u) const {
;         const long L = (long)i * G + c; if (L >= nwg) return false;
; __global__ void __launch_bounds__(512, 2) trunk_fwd(Args a0) {
;     ...
;                 const int rot = (E.kind == K_KV) ? 134 : (E.kind == K_VT) ? 138 : 0;
;                 pg8::StaticOrder S; S.init(g.M, g.N, G, (bx + G - rot % G) % G); pg8::gemm_phase(lds, g, S, E, wv);
.LBB0_249:
	v_readlane_b32 s2, v253, 28
	s_mul_hi_u32 s0, s8, s2
	s_mul_i32 s0, s0, s99
	s_sub_i32 s0, s8, s0
	s_sub_i32 s1, s0, s99
	s_cmp_ge_u32 s0, s99
	s_cselect_b32 s0, s1, s0
	s_sub_i32 s1, s0, s99
	s_cmp_ge_u32 s0, s99
	s_cselect_b32 s0, s1, s0
	s_sub_i32 s0, s89, s0
	s_ashr_i32 s1, s0, 31
	s_abs_i32 s0, s0
	s_mul_hi_u32 s4, s0, s2
	s_mul_i32 s4, s4, s99
	s_sub_i32 s0, s0, s4
	s_sub_i32 s4, s0, s99
	s_cmp_ge_u32 s0, s99
	s_cselect_b32 s0, s4, s0
	s_sub_i32 s4, s0, s99
	s_cmp_ge_u32 s0, s99
	s_cselect_b32 s0, s4, s0
	s_xor_b32 s0, s0, s1
	s_sub_i32 s70, s0, s1
	s_mul_i32 s84, s96, s18
	s_mov_b32 s100, s33
	s_mov_b32 s101, s84
	s_cmpk_lg_i32 s33, 0x100
	s_cbranch_scc1 .Lkvbal_done
	s_cmp_eq_u32 s35, 2
	s_cselect_b32 s0, 1, 0
	s_cmp_eq_u32 s35, 6
	s_cselect_b32 s0, 1, s0
	s_cmp_eq_u32 s0, 0
	s_cbranch_scc1 .Lkvbal_done
	s_sub_i32 s0, s89, s33
	s_movk_i32 s70, 0x104
	s_sub_i32 s1, s0, 0x86
	s_cmp_ge_i32 s0, 0x86
	s_cbranch_scc0 .Lkvbal_done
	s_mov_b32 s70, s1
	s_movk_i32 s100, 0x7a
.Lkvbal_done:
	s_waitcnt vmcnt(0)
	v_mov_b32_e32 v20, v228
	s_cmp_lt_i32 s70, s101
	s_cselect_b64 s[0:1], -1, 0
	v_readfirstlane_b32 s17, v20
	s_cmp_ge_i32 s70, s101
	s_cbranch_scc1 .LBB0_255
	s_ashr_i32 s4, s70, 31
	s_lshr_b32 s4, s4, 29
	s_add_i32 s8, s70, s4
	s_lshr_b32 s19, s84, 3
	s_and_b32 s4, s8, -8
	s_and_b32 s20, s84, 6
	s_sub_i32 s14, s70, s4
	s_add_i32 s15, s19, 1
	s_cmp_ge_i32 s14, s20
	s_mov_b64 s[4:5], -1
	s_cbranch_scc0 .LBB0_252
	s_sub_i32 s5, s14, s20
	s_mul_i32 s4, s15, s20
	s_mul_i32 s5, s5, s19
	s_add_i32 s13, s5, s4
	s_mov_b64 s[4:5], 0

;     __device__ bool next(int i, Unit& u) const {
;         const long L = (long)i * G + c; if (L >= nwg) return false;
;         int wgid = (int)L; { const int q = nwg / NXCD, r = nwg % NXCD, xcd = wgid % NXCD, off = wgid / NXCD; wgid = (xcd < r ? xcd * (q + 1) : r * (q + 1) + (xcd - r) * q) + off; }
; template <class EpiT>
; __device__ __forceinline__ void gemm_phase(LAS unsigned char* lds, const Gemm g, const StaticOrder& S, const EpiT& E, int wv) {
;     ...
;         const bool has_next = S.next(ui + 1, nxt);
.LBB0_261:
	s_add_i32 s53, s53, 1
	s_mul_i32 s0, s53, s28
	s_mul_hi_u32 s1, s53, s100
	s_add_i32 s1, s1, s0
	s_mul_i32 s0, s53, s100
	s_add_u32 s18, s0, s70
	s_addc_u32 s19, s1, s54
	v_mov_b32_e32 v6, s101
	v_mov_b32_e32 v7, s85
	v_cmp_ge_i64_e32 vcc, s[18:19], v[6:7]
	v_cmp_lt_i64_e64 s[0:1], s[18:19], v[6:7]
	s_cbranch_vccnz .LBB0_267
	s_ashr_i32 s5, s18, 31
	s_lshr_b32 s5, s5, 29
	s_add_i32 s5, s18, s5
	s_and_b32 s19, s5, -8
	s_sub_i32 s20, s18, s19
	s_cmp_ge_i32 s20, s56
	s_mov_b64 s[18:19], -1
	s_cbranch_scc0 .LBB0_264
	s_sub_i32 s18, s20, s56
	v_readlane_b32 s2, v255, 36
	s_mul_i32 s18, s18, s2
	s_mul_i32 s19, s99, s56
	s_add_i32 s21, s18, s19
	s_mov_b64 s[18:19], 0
